# prologue f32 weight rows loaded with nt policy
# speedup vs baseline: 1.0228x; 1.0082x over previous
.LBB0_43:
	s_andn2_b64 vcc, exec, s[18:19]
	s_cbranch_vccnz .LBB0_9
	s_lshr_b32 s4, s36, 7
	v_cvt_f32_u32_e32 v2, s4
	s_sub_i32 s15, 0, s4
	s_sub_i32 s5, s23, s42
	s_abs_i32 s14, s5
	v_rcp_iflag_f32_e32 v2, v2
	s_ashr_i32 s6, s5, 31
	v_mov_b32_e32 v13, v9
	v_mul_f32_e32 v2, 0x4f7ffffe, v2
	v_cvt_u32_f32_e32 v2, v2
	s_nop 0
	v_readfirstlane_b32 s16, v2
	s_mul_i32 s15, s15, s16
	s_mul_hi_u32 s15, s16, s15
	s_add_i32 s16, s16, s15
	s_mul_hi_u32 s15, s14, s16
	s_mul_i32 s16, s15, s4
	s_sub_i32 s14, s14, s16
	s_add_i32 s17, s15, 1
	s_sub_i32 s16, s14, s4
	s_cmp_ge_u32 s14, s4
	s_cselect_b32 s15, s17, s15
	s_cselect_b32 s14, s16, s14
	s_add_i32 s16, s15, 1
	s_cmp_ge_u32 s14, s4
	s_cselect_b32 s14, s16, s15
	s_xor_b32 s14, s14, s6
	s_sub_i32 s6, s14, s6
	s_mul_i32 s4, s6, s4
	s_sub_i32 s4, s5, s4
	s_lshl_b32 s16, s4, 7
	s_ashr_i32 s17, s16, 31
	s_lshl_b32 s14, s6, 7
	s_lshl_b64 s[4:5], s[16:17], 2
	s_add_u32 s4, s8, s4
	v_add_u32_e32 v16, s14, v7
	s_addc_u32 s5, s9, s5
	v_lshl_add_u64 v[14:15], s[4:5], 0, v[12:13]
	v_mad_u64_u32 v[2:3], s[4:5], v16, s36, 0
	v_ashrrev_i32_e32 v17, 31, v16
	v_mov_b32_e32 v4, v3
	v_mad_u64_u32 v[4:5], s[4:5], v17, s36, v[4:5]
	v_mov_b32_e32 v3, v4
	v_lshl_add_u64 v[2:3], v[2:3], 2, v[14:15]
	s_lshl_b32 s4, s36, 6
	s_mov_b32 s5, 0
	global_load_dwordx4 v[28:31], v[2:3], off nt
	v_lshl_add_u64 v[2:3], v[2:3], 0, s[4:5]
	global_load_dwordx4 v[32:35], v[2:3], off nt
	v_lshl_add_u64 v[2:3], v[2:3], 0, s[4:5]
	global_load_dwordx4 v[36:39], v[2:3], off nt
	v_lshl_add_u64 v[2:3], v[2:3], 0, s[4:5]
	global_load_dwordx4 v[40:43], v[2:3], off nt
	v_lshl_add_u64 v[2:3], v[2:3], 0, s[4:5]
	global_load_dwordx4 v[44:47], v[2:3], off nt
	v_lshl_add_u64 v[2:3], v[2:3], 0, s[4:5]
	global_load_dwordx4 v[48:51], v[2:3], off nt
	v_lshl_add_u64 v[2:3], v[2:3], 0, s[4:5]
	global_load_dwordx4 v[52:55], v[2:3], off nt
	v_lshl_add_u64 v[2:3], v[2:3], 0, s[4:5]
	global_load_dwordx4 v[56:59], v[2:3], off nt
	v_lshl_add_u64 v[18:19], v[16:17], 2, s[12:13]
	s_cmp_eq_u64 s[12:13], 0
	s_cbranch_scc1 .Ltr_nogain
	global_load_dword v60, v[18:19], off
	global_load_dword v61, v[18:19], off offset:64
	global_load_dword v62, v[18:19], off offset:128
	global_load_dword v63, v[18:19], off offset:192
	global_load_dword v64, v[18:19], off offset:256
	global_load_dword v65, v[18:19], off offset:320
	global_load_dword v66, v[18:19], off offset:384
	global_load_dword v67, v[18:19], off offset:448
	s_branch .Ltr_gain_done
